# rwkv_pre writes the 16-byte pieces of each Z unit write-through (sc0 sc1) so the mid-phase barrier has less dirty L2 to flush
# baseline (speedup 1.0000x reference)
.LBB0_804:
	s_or_b64 exec, exec, s[10:11]
	s_waitcnt lgkmcnt(0)
	v_add_f32_e32 v203, v203, v204
	v_mul_f32_e32 v204, 0x4f800000, v203
	v_cmp_gt_f32_e32 vcc, s51, v203
	v_sub_f32_e32 v225, v226, v225
	v_mul_f32_e32 v225, 0x3fb8aa3b, v225
	v_cndmask_b32_e32 v203, v203, v204, vcc
	v_sqrt_f32_e32 v204, v203
	v_exp_f32_e32 v225, v225
	v_mul_f32_e32 v226, 0xbfb8aa3b, v226
	v_exp_f32_e32 v226, v226
	v_add_u32_e32 v227, -1, v204
	v_fma_f32 v229, -v227, v204, v203
	v_add_u32_e32 v228, 1, v204
	v_cmp_ge_f32_e64 s[20:21], 0, v229
	s_nop 1
	v_cndmask_b32_e64 v227, v204, v227, s[20:21]
	v_fma_f32 v204, -v228, v204, v203
	v_cmp_lt_f32_e64 s[20:21], 0, v204
	s_nop 1
	v_cndmask_b32_e64 v204, v227, v228, s[20:21]
	v_mul_f32_e32 v227, 0x37800000, v204
	v_cndmask_b32_e32 v204, v204, v227, vcc
	v_cmp_class_f32_e32 vcc, v203, v172
	s_nop 1
	v_cndmask_b32_e32 v203, v204, v203, vcc
	v_max_f32_e32 v203, 0x2b8cbccc, v203
	v_div_scale_f32 v204, s[10:11], v203, v203, 1.0
	v_rcp_f32_e32 v227, v204
	s_lshr_b32 s10, s29, 8
	s_lshl_b32 s11, s3, 5
	s_add_i32 s10, s10, s11
	s_mul_hi_i32 s11, s10, 0x3200
	s_mulk_i32 s10, 0x3200
	v_fma_f32 v228, -v204, v227, 1.0
	v_fmac_f32_e32 v227, v228, v227
	v_div_scale_f32 v228, vcc, 1.0, v203, 1.0
	v_mul_f32_e32 v229, v228, v227
	v_fma_f32 v230, -v204, v229, v228
	v_fmac_f32_e32 v229, v230, v227
	v_fma_f32 v204, -v204, v229, v228
	v_div_fmas_f32 v204, v204, v227, v229
	v_div_fixup_f32 v203, v204, v203, 1.0
	v_and_b32_e32 v204, 0xffff0000, v83
	v_and_b32_e32 v227, 0xffff0000, v85
	s_waitcnt vmcnt(0)
	v_and_b32_e32 v228, 0xffff0000, v87
	v_fma_f32 v227, v96, v227, -v204
	v_fmac_f32_e32 v204, v15, v227
	v_add_f32_e32 v227, -1.0, v228
	v_lshlrev_b32_e32 v83, 16, v83
	v_lshlrev_b32_e32 v85, 16, v85
	v_fma_f32 v227, v19, v227, 1.0
	v_mul_f32_e32 v199, v199, v203
	v_lshlrev_b32_e32 v87, 16, v87
	v_fma_f32 v85, v96, v85, -v83
	v_mul_f32_e32 v131, v131, v227
	v_mul_f32_e32 v225, v199, v225
	v_mul_f32_e32 v199, v199, v228
	v_fmac_f32_e32 v83, v14, v85
	v_add_f32_e32 v85, -1.0, v87
	v_mul_f32_e32 v199, v199, v226
	v_mul_f32_e32 v226, v131, v226
	v_mul_f32_e32 v131, v204, v89
	v_fma_f32 v85, v18, v85, 1.0
	v_sub_f32_e32 v89, v224, v223
	v_mul_f32_e32 v85, v130, v85
	v_mul_f32_e32 v89, 0x3fb8aa3b, v89
	v_mul_f32_e32 v130, 0xbfb8aa3b, v224
	v_exp_f32_e32 v89, v89
	v_exp_f32_e32 v130, v130
	v_mul_f32_e32 v198, v198, v203
	v_mul_f32_e32 v87, v198, v87
	v_mul_f32_e32 v204, v198, v89
	v_mul_f32_e32 v198, v87, v130
	v_mul_f32_e32 v223, v85, v130
	v_mul_f32_e32 v130, v83, v222
	v_and_b32_e32 v83, 0xffff0000, v82
	v_and_b32_e32 v85, 0xffff0000, v84
	v_and_b32_e32 v87, 0xffff0000, v86
	v_fma_f32 v85, v96, v85, -v83
	v_fmac_f32_e32 v83, v13, v85
	v_add_f32_e32 v85, -1.0, v87
	v_fma_f32 v85, v17, v85, 1.0
	v_sub_f32_e32 v89, v221, v220
	v_mul_f32_e32 v85, v135, v85
	v_mul_f32_e32 v89, 0x3fb8aa3b, v89
	v_mul_f32_e32 v135, 0xbfb8aa3b, v221
	v_exp_f32_e32 v89, v89
	v_exp_f32_e32 v135, v135
	v_mul_f32_e32 v195, v195, v203
	v_mul_f32_e32 v87, v195, v87
	v_mul_f32_e32 v220, v195, v89
	v_mul_f32_e32 v195, v87, v135
	v_mul_f32_e32 v221, v85, v135
	v_mul_f32_e32 v135, v83, v88
	v_lshlrev_b32_e32 v82, 16, v82
	v_lshlrev_b32_e32 v83, 16, v84
	v_lshlrev_b32_e32 v84, 16, v86
	v_mul_f32_e32 v86, 0xbfb8aa3b, v219
	v_fma_f32 v83, v96, v83, -v82
	v_exp_f32_e32 v86, v86
	v_fmac_f32_e32 v82, v12, v83
	v_add_f32_e32 v83, -1.0, v84
	v_fma_f32 v83, v16, v83, 1.0
	v_mul_f32_e32 v87, v194, v203
	v_mul_f32_e32 v83, v134, v83
	v_sub_f32_e32 v85, v219, v218
	v_mul_f32_e32 v84, v87, v84
	v_mul_f32_e32 v85, 0x3fb8aa3b, v85
	v_mul_f32_e32 v218, v84, v86
	v_mul_f32_e32 v219, v83, v86
	v_mul_f32_e32 v134, v82, v217
	v_and_b32_e32 v82, 0xffff0000, v75
	v_and_b32_e32 v83, 0xffff0000, v77
	v_mul_f32_e32 v86, 0xbfb8aa3b, v216
	v_exp_f32_e32 v85, v85
	v_and_b32_e32 v84, 0xffff0000, v81
	v_fma_f32 v83, v96, v83, -v82
	v_exp_f32_e32 v86, v86
	v_fmac_f32_e32 v82, v11, v83
	v_add_f32_e32 v83, -1.0, v84
	v_fma_f32 v83, v27, v83, 1.0
	v_mul_f32_e32 v83, v137, v83
	v_mul_f32_e32 v137, v82, v91
	v_sub_f32_e32 v82, v214, v213
	v_mul_f32_e32 v194, v87, v85
	v_sub_f32_e32 v85, v216, v215
	v_mul_f32_e32 v215, v83, v86
	v_mul_f32_e32 v82, 0x3fb8aa3b, v82
	v_mul_f32_e32 v83, 0xbfb8aa3b, v214
	v_mul_f32_e32 v87, v190, v203
	v_lshlrev_b32_e32 v75, 16, v75
	v_lshlrev_b32_e32 v77, 16, v77
	v_exp_f32_e32 v82, v82
	v_exp_f32_e32 v83, v83
	v_mul_f32_e32 v84, v87, v84
	v_lshlrev_b32_e32 v81, 16, v81
	v_fma_f32 v77, v96, v77, -v75
	v_mul_f32_e32 v190, v84, v86
	v_fmac_f32_e32 v75, v10, v77
	v_add_f32_e32 v77, -1.0, v81
	v_mul_f32_e32 v84, v187, v203
	v_fma_f32 v77, v26, v77, 1.0
	v_mul_f32_e32 v81, v84, v81
	v_mul_f32_e32 v77, v136, v77
	v_mul_f32_e32 v91, v84, v82
	v_mul_f32_e32 v187, v81, v83
	v_mul_f32_e32 v136, v75, v212
	v_and_b32_e32 v75, 0xffff0000, v74
	v_and_b32_e32 v81, 0xffff0000, v76
	v_mul_f32_e32 v84, 0xbfb8aa3b, v211
	v_and_b32_e32 v82, 0xffff0000, v80
	v_fma_f32 v81, v96, v81, -v75
	v_exp_f32_e32 v84, v84
	v_mul_f32_e32 v85, 0x3fb8aa3b, v85
	v_fmac_f32_e32 v75, v9, v81
	v_add_f32_e32 v81, -1.0, v82
	v_exp_f32_e32 v85, v85
	v_fma_f32 v81, v25, v81, 1.0
	v_mul_f32_e32 v81, v139, v81
	v_mul_f32_e32 v77, v77, v83
	v_sub_f32_e32 v83, v211, v210
	v_mul_f32_e32 v210, v81, v84
	v_mul_f32_e32 v139, v75, v90
	v_lshlrev_b32_e32 v74, 16, v74
	v_lshlrev_b32_e32 v75, 16, v76
	v_lshlrev_b32_e32 v76, 16, v80
	v_sub_f32_e32 v80, v209, v208
	v_mul_f32_e32 v81, 0xbfb8aa3b, v209
	v_fma_f32 v75, v96, v75, -v74
	v_mul_f32_e32 v80, 0x3fb8aa3b, v80
	v_exp_f32_e32 v81, v81
	v_mul_f32_e32 v89, v87, v85
	v_mul_f32_e32 v85, v186, v203
	v_fmac_f32_e32 v74, v8, v75
	v_add_f32_e32 v75, -1.0, v76
	v_exp_f32_e32 v80, v80
	v_mul_f32_e32 v82, v85, v82
	v_fma_f32 v75, v24, v75, 1.0
	v_mul_f32_e32 v186, v82, v84
	v_mul_f32_e32 v75, v138, v75
	v_mul_f32_e32 v82, v184, v203
	v_mul_f32_e32 v83, 0x3fb8aa3b, v83
	v_mul_f32_e32 v76, v82, v76
	v_mul_f32_e32 v184, v75, v81
	v_mul_f32_e32 v138, v74, v207
	v_and_b32_e32 v74, 0xffff0000, v69
	v_and_b32_e32 v75, 0xffff0000, v71
	v_exp_f32_e32 v83, v83
	v_mul_f32_e32 v90, v82, v80
	v_mul_f32_e32 v76, v76, v81
	v_and_b32_e32 v80, 0xffff0000, v79
	v_fma_f32 v75, v96, v75, -v74
	v_sub_f32_e32 v81, v206, v205
	v_fmac_f32_e32 v74, v7, v75
	v_add_f32_e32 v75, -1.0, v80
	v_mul_f32_e32 v81, 0x3fb8aa3b, v81
	v_mul_f32_e32 v82, 0xbfb8aa3b, v206
	v_fma_f32 v75, v43, v75, 1.0
	v_exp_f32_e32 v81, v81
	v_exp_f32_e32 v82, v82
	v_mul_f32_e32 v75, v141, v75
	v_mul_f32_e32 v141, v74, v95
	v_lshlrev_b32_e32 v69, 16, v69
	v_lshlrev_b32_e32 v71, 16, v71
	v_lshlrev_b32_e32 v74, 16, v79
	v_mul_f32_e32 v79, 0xbfb8aa3b, v202
	v_mul_f32_e32 v88, v85, v83
	v_mul_f32_e32 v83, v181, v203
	v_fma_f32 v71, v96, v71, -v69
	v_exp_f32_e32 v79, v79
	v_mul_f32_e32 v80, v83, v80
	v_fmac_f32_e32 v69, v6, v71
	v_add_f32_e32 v71, -1.0, v74
	v_mul_f32_e32 v86, v83, v81
	v_mul_f32_e32 v83, v80, v82
	v_mul_f32_e32 v87, v75, v82
	v_fma_f32 v71, v42, v71, 1.0
	v_sub_f32_e32 v75, v202, v201
	v_mul_f32_e32 v80, v178, v203
	v_mul_f32_e32 v71, v140, v71
	v_mul_f32_e32 v75, 0x3fb8aa3b, v75
	v_mul_f32_e32 v74, v80, v74
	v_exp_f32_e32 v75, v75
	v_mul_f32_e32 v95, v74, v79
	v_mul_f32_e32 v178, v71, v79
	v_mul_f32_e32 v140, v69, v200
	v_and_b32_e32 v69, 0xffff0000, v68
	v_and_b32_e32 v71, 0xffff0000, v70
	v_mul_f32_e32 v79, 0xbfb8aa3b, v197
	v_and_b32_e32 v74, 0xffff0000, v78
	v_fma_f32 v71, v96, v71, -v69
	v_exp_f32_e32 v79, v79
	v_fmac_f32_e32 v69, v5, v71
	v_add_f32_e32 v71, -1.0, v74
	v_fma_f32 v71, v41, v71, 1.0
	v_mul_f32_e32 v82, v80, v75
	v_mul_f32_e32 v71, v176, v71
	v_sub_f32_e32 v75, v197, v196
	v_mul_f32_e32 v80, v177, v203
	v_mul_f32_e32 v75, 0x3fb8aa3b, v75
	v_mul_f32_e32 v74, v80, v74
	v_mul_f32_e32 v181, v71, v79
	v_sub_f32_e32 v71, v193, v192
	v_exp_f32_e32 v75, v75
	v_mul_f32_e32 v177, v74, v79
	v_mul_f32_e32 v79, v69, v94
	v_lshlrev_b32_e32 v68, 16, v68
	v_lshlrev_b32_e32 v69, 16, v70
	v_mul_f32_e32 v71, 0x3fb8aa3b, v71
	v_mul_f32_e32 v74, 0xbfb8aa3b, v193
	v_lshlrev_b32_e32 v70, 16, v78
	v_fma_f32 v69, v96, v69, -v68
	v_exp_f32_e32 v71, v71
	v_exp_f32_e32 v74, v74
	v_fmac_f32_e32 v68, v4, v69
	v_add_f32_e32 v69, -1.0, v70
	v_fma_f32 v69, v40, v69, 1.0
	v_mul_f32_e32 v176, v80, v75
	v_mul_f32_e32 v69, v149, v69
	v_mul_f32_e32 v75, v151, v203
	v_mul_f32_e32 v71, v75, v71
	v_mul_f32_e32 v70, v75, v70
	v_mul_f32_e32 v149, v69, v74
	v_mul_f32_e32 v78, v68, v191
	v_and_b32_e32 v68, 0xffff0000, v65
	v_and_b32_e32 v69, 0xffff0000, v67
	v_mul_f32_e32 v75, 0xbfb8aa3b, v189
	v_mul_f32_e32 v94, v70, v74
	v_and_b32_e32 v70, 0xffff0000, v73
	v_fma_f32 v69, v96, v69, -v68
	v_exp_f32_e32 v75, v75
	v_fmac_f32_e32 v68, v3, v69
	v_add_f32_e32 v69, -1.0, v70
	v_fma_f32 v69, v51, v69, 1.0
	v_sub_f32_e32 v74, v189, v188
	v_mul_f32_e32 v69, v143, v69
	v_mul_f32_e32 v74, 0x3fb8aa3b, v74
	v_mul_f32_e32 v80, v148, v203
	v_exp_f32_e32 v74, v74
	v_mul_f32_e32 v70, v80, v70
	v_mul_f32_e32 v85, v69, v75
	v_sub_f32_e32 v69, v185, v183
	v_mul_f32_e32 v70, v70, v75
	v_mul_f32_e32 v75, v68, v93
	v_lshlrev_b32_e32 v68, 16, v73
	v_mul_f32_e32 v69, 0x3fb8aa3b, v69
	v_mul_f32_e32 v73, 0xbfb8aa3b, v185
	v_lshlrev_b32_e32 v65, 16, v65
	v_lshlrev_b32_e32 v67, 16, v67
	v_exp_f32_e32 v69, v69
	v_exp_f32_e32 v73, v73
	v_fma_f32 v67, v96, v67, -v65
	v_mul_f32_e32 v81, v80, v74
	v_fmac_f32_e32 v65, v2, v67
	v_add_f32_e32 v67, -1.0, v68
	v_mul_f32_e32 v74, v142, v203
	v_fma_f32 v67, v50, v67, 1.0
	v_mul_f32_e32 v68, v74, v68
	v_mul_f32_e32 v67, v129, v67
	v_mul_f32_e32 v69, v74, v69
	v_mul_f32_e32 v84, v68, v73
	v_mul_f32_e32 v74, v65, v182
	v_and_b32_e32 v65, 0xffff0000, v64
	v_and_b32_e32 v68, 0xffff0000, v66
	v_mul_f32_e32 v67, v67, v73
	v_and_b32_e32 v73, 0xffff0000, v72
	v_fma_f32 v68, v96, v68, -v65
	v_mul_f32_e32 v93, 0xbfb8aa3b, v180
	v_fmac_f32_e32 v65, v1, v68
	v_add_f32_e32 v68, -1.0, v73
	v_exp_f32_e32 v93, v93
	v_fma_f32 v68, v49, v68, 1.0
	v_mul_f32_e32 v68, v125, v68
	v_sub_f32_e32 v80, v180, v179
	v_mul_f32_e32 v125, v127, v203
	v_mul_f32_e32 v143, v65, v92
	v_lshlrev_b32_e32 v65, 16, v72
	v_sub_f32_e32 v72, v175, v150
	v_mul_f32_e32 v80, 0x3fb8aa3b, v80
	v_mul_f32_e32 v73, v125, v73
	v_mul_f32_e32 v72, 0x3fb8aa3b, v72
	v_mul_f32_e32 v92, 0xbfb8aa3b, v175
	v_exp_f32_e32 v80, v80
	v_mul_f32_e32 v73, v73, v93
	v_mul_f32_e32 v93, v68, v93
	v_add_f32_e32 v68, -1.0, v65
	v_exp_f32_e32 v72, v72
	v_exp_f32_e32 v92, v92
	v_fma_f32 v68, v48, v68, 1.0
	v_mul_f32_e32 v68, v98, v68
	v_mul_f32_e32 v98, v99, v203
	v_mul_f32_e32 v65, v98, v65
	v_mul_f32_e32 v80, v125, v80
	v_mul_f32_e32 v72, v72, v98
	v_mul_f32_e32 v65, v92, v65
	v_mul_f32_e32 v92, v68, v92
	v_cvt_pk_bf16_f32 v68, v72, v80
	v_cvt_pk_bf16_f32 v69, v69, v81
	v_cvt_pk_bf16_f32 v80, v65, v73
	v_cvt_pk_bf16_f32 v81, v84, v70
	v_cvt_pk_bf16_f32 v70, v71, v176
	v_cvt_pk_bf16_f32 v71, v82, v86
	v_cvt_pk_bf16_f32 v82, v94, v177
	v_cvt_pk_bf16_f32 v83, v95, v83
	v_lshlrev_b32_e32 v72, 16, v64
	v_lshlrev_b32_e32 v64, 16, v66
	v_fma_f32 v73, v96, v64, -v72
	v_fmac_f32_e32 v72, v0, v73
	v_cvt_pk_bf16_f32 v84, v92, v93
	v_cvt_pk_bf16_f32 v92, v76, v186
	v_cvt_pk_bf16_f32 v93, v187, v190
	v_cvt_pk_bf16_f32 v94, v218, v195
	v_cvt_pk_bf16_f32 v95, v198, v199
	v_mul_f32_e32 v142, v72, v97
	v_cvt_pk_bf16_f32 v85, v67, v85
	v_cvt_pk_bf16_f32 v86, v149, v181
	v_cvt_pk_bf16_f32 v87, v178, v87
	v_cvt_pk_bf16_f32 v88, v90, v88
	v_cvt_pk_bf16_f32 v89, v91, v89
	v_cvt_pk_bf16_f32 v90, v194, v220
	v_cvt_pk_bf16_f32 v91, v204, v225
	v_mfma_f32_16x16x32_bf16 v[180:183], v[80:83], v[68:71], 0
	v_add_u32_e32 v72, 0x800, v155
	v_cvt_pk_bf16_f32 v96, v142, v143
	v_cvt_pk_bf16_f32 v97, v74, v75
	v_cvt_pk_bf16_f32 v98, v78, v79
	v_cvt_pk_bf16_f32 v99, v140, v141
	v_mfma_f32_16x16x32_bf16 v[176:179], v[68:71], v[84:87], 0
	ds_write2_b64 v155, v[68:69], v[70:71] offset1:4
	ds_write2_b64 v72, v[80:81], v[82:83] offset0:16 offset1:20
	v_add_u32_e32 v73, 0x1000, v155
	v_mfma_f32_16x16x32_bf16 v[68:71], v[68:71], v[80:83], 0
	v_cvt_pk_bf16_f32 v148, v184, v210
	v_cvt_pk_bf16_f32 v149, v77, v215
	v_cvt_pk_bf16_f32 v150, v219, v221
	v_mfma_f32_16x16x32_bf16 v[80:83], v[80:83], v[96:99], 0
	v_cvt_pk_bf16_f32 v151, v223, v226
	ds_write2_b64 v73, v[84:85], v[86:87] offset0:32 offset1:36
	ds_write2_b64 v155, v[88:89], v[90:91] offset0:8 offset1:12
	ds_write2_b64 v72, v[92:93], v[94:95] offset0:24 offset1:28
	ds_write2_b64 v73, v[148:149], v[150:151] offset0:40 offset1:44
	v_mfma_f32_16x16x32_bf16 v[64:67], v[92:95], v[88:91], v[180:183]
	s_waitcnt lgkmcnt(0)
	v_mov_b32_e32 v190, v103
	v_mov_b32_e32 v191, v103
	v_mfma_f32_16x16x32_bf16 v[68:71], v[88:91], v[92:95], v[68:71]
	v_cvt_pk_bf16_f32 v180, v138, v139
	v_cvt_pk_bf16_f32 v181, v136, v137
	v_cvt_pk_bf16_f32 v182, v134, v135
	v_cvt_pk_bf16_f32 v183, v130, v131
	v_mfma_f32_16x16x32_bf16 v[184:187], v[84:87], v[96:99], 0
	v_cndmask_b32_e64 v73, 0, -v64, s[6:7]
	s_nop 1
	v_cndmask_b32_e64 v68, 0, -v68, s[4:5]
	v_cndmask_b32_e64 v69, -v69, 0, s[6:7]
	v_mfma_f32_16x16x32_bf16 v[80:83], v[92:95], v[180:183], v[80:83]
	v_cndmask_b32_e64 v85, 0, -v66, s[14:15]
	v_cndmask_b32_e64 v70, 0, -v70, s[12:13]
	v_cndmask_b32_e64 v67, 0, -v67, s[18:19]
	v_cndmask_b32_e64 v92, 0, -v71, s[16:17]
	v_add_f32_e32 v64, v110, v68
	s_nop 2
	v_cndmask_b32_e64 v76, v80, 0, s[4:5]
	v_cndmask_b32_e64 v80, 0, -v65, s[8:9]
	v_add_f32_e32 v65, v111, v69
	v_add_f32_e32 v66, v112, v70
	v_cvt_pk_bf16_f32 v68, v68, v69
	v_cvt_pk_bf16_f32 v69, v70, v92
	v_mov_b32_e32 v70, v103
	v_mov_b32_e32 v71, v103
	v_cvt_pk_bf16_f32 v84, v73, v80
	v_cvt_pk_bf16_f32 v85, v85, v67
	v_mov_b32_e32 v86, v103
	v_mov_b32_e32 v87, v103
	v_mfma_f32_16x16x32_bf16 v[176:179], v[88:91], v[148:151], v[176:179]
	v_add_f32_e32 v67, v113, v92
	v_cvt_pk_bf16_f32 v92, v64, v65
	v_cvt_pk_bf16_f32 v93, v66, v67
	v_mfma_f32_16x16x32_bf16 v[88:91], v[68:71], v[84:87], 0
	v_mov_b32_e32 v94, v103
	v_mov_b32_e32 v95, v103
	v_cndmask_b32_e64 v73, 0, v81, s[6:7]
	v_mfma_f32_16x16x32_bf16 v[68:71], v[84:87], v[68:71], 0
	v_cndmask_b32_e64 v97, v82, 0, s[12:13]
	s_nop 2
	v_cvt_pk_bf16_f32 v84, v88, v89
	v_cvt_pk_bf16_f32 v85, v90, v91
	v_mov_b32_e32 v82, v103
	v_mfma_f32_16x16x32_bf16 v[184:187], v[148:151], v[180:183], v[184:187]
	v_cvt_pk_bf16_f32 v68, v68, v69
	v_cvt_pk_bf16_f32 v69, v70, v71
	v_mov_b32_e32 v70, v103
	v_mov_b32_e32 v71, v103
	v_mfma_f32_16x16x32_bf16 v[64:67], v[84:87], v[92:95], v[64:67]
	v_cndmask_b32_e64 v72, 0, v176, s[4:5]
	v_cndmask_b32_e64 v77, v177, 0, s[6:7]
	v_cndmask_b32_e64 v96, 0, v178, s[12:13]
	v_mfma_f32_16x16x32_bf16 v[88:91], v[68:71], v[84:87], 0
	v_cndmask_b32_e64 v129, v186, 0, s[12:13]
	s_nop 2
	v_cvt_pk_bf16_f32 v92, v64, v65
	v_cvt_pk_bf16_f32 v93, v66, v67
	v_mfma_f32_16x16x32_bf16 v[68:71], v[84:87], v[68:71], 0
	v_cndmask_b32_e64 v175, v187, 0, s[16:17]
	v_cvt_pk_bf16_f32 v84, v88, v89
	v_cvt_pk_bf16_f32 v85, v90, v91
	v_cndmask_b32_e64 v90, v83, 0, s[16:17]
	v_mov_b32_e32 v83, v103
	s_nop 2
	v_cvt_pk_bf16_f32 v68, v68, v69
	v_cvt_pk_bf16_f32 v69, v70, v71
	v_mov_b32_e32 v70, v103
	v_mov_b32_e32 v71, v103
	v_mfma_f32_16x16x32_bf16 v[64:67], v[84:87], v[92:95], v[64:67]
	v_cndmask_b32_e64 v89, 0, v179, s[16:17]
	v_cvt_pk_bf16_f32 v88, v72, v77
	v_cvt_pk_bf16_f32 v89, v96, v89
	v_mfma_f32_16x16x32_bf16 v[68:71], v[68:71], v[84:87], 0
	v_cndmask_b32_e64 v125, v184, 0, s[4:5]
	s_nop 2
	v_cvt_pk_bf16_f32 v80, v64, v65
	v_cvt_pk_bf16_f32 v81, v66, v67
	v_cndmask_b32_e64 v127, 0, v185, s[6:7]
	v_mov_b32_e32 v91, v103
	v_cvt_pk_bf16_f32 v68, v68, v69
	v_cvt_pk_bf16_f32 v69, v70, v71
	v_mov_b32_e32 v70, v103
	v_mov_b32_e32 v71, v103
	s_add_u32 s20, s35, s10
	s_addc_u32 s21, s42, s11
	v_mfma_f32_16x16x32_bf16 v[64:67], v[68:71], v[80:83], v[64:67]
	s_add_u32 s10, s20, 0x2800
	s_addc_u32 s11, s21, 0
	s_add_i32 s3, s43, s3
	s_nop 4
	v_cvt_pk_bf16_f32 v92, v64, v65
	v_cvt_pk_bf16_f32 v93, v66, v67
	v_cvt_pk_bf16_f32 v64, v76, v73
	v_cvt_pk_bf16_f32 v65, v97, v90
	v_mov_b32_e32 v66, v103
	v_mov_b32_e32 v67, v103
	v_mov_b32_e32 v90, v103
	s_cmpk_lt_i32 s3, 0x100
	v_mfma_f32_16x16x32_bf16 v[64:67], v[92:95], v[64:67], 0
	s_nop 7
	v_cvt_pk_bf16_f32 v84, v64, v65
	v_cvt_pk_bf16_f32 v85, v66, v67
	ds_read_u16 v64, v156
	ds_read_u16 v66, v156 offset:2176
	ds_read_u16 v67, v157
	ds_read_u16 v68, v157 offset:2176
	ds_read_u16 v65, v158
	ds_read_u16 v69, v158 offset:2176
	ds_read_u16 v70, v157 offset:4352
	ds_read_u16 v71, v159
	ds_read_u16 v72, v159 offset:2176
	ds_read_u16 v73, v160
	ds_read_u16 v76, v160 offset:2176
	ds_read_u16 v77, v161
	ds_read_u16 v182, v160 offset:4352
	ds_read_u16 v178, v159 offset:4352
	ds_read_u16 v179, v158 offset:4352
	s_waitcnt lgkmcnt(11)
	v_perm_b32 v96, v68, v66, s52
	v_add_u32_e32 v66, 0x1800, v154
	s_waitcnt lgkmcnt(7)
	v_perm_b32 v65, v71, v65, s52
	ds_read_u16 v71, v156 offset:4352
	v_perm_b32 v64, v67, v64, s52
	s_waitcnt lgkmcnt(7)
	v_perm_b32 v97, v72, v69, s52
	ds_read2_b32 v[150:151], v66 offset0:96 offset1:112
	ds_read_u16 v67, v161 offset:2176
	ds_read_u16 v68, v162
	ds_read_u16 v72, v162 offset:2176
	ds_read_u16 v69, v163
	ds_read_u16 v98, v163 offset:2176
	ds_read_u16 v183, v163 offset:4352
	ds_read_u16 v186, v162 offset:4352
	ds_read_u16 v187, v161 offset:4352
	s_waitcnt lgkmcnt(4)
	v_perm_b32 v69, v69, v68, s52
	v_perm_b32 v68, v77, v73, s52
	s_waitcnt lgkmcnt(3)
	v_perm_b32 v177, v98, v72, s52
	v_perm_b32 v176, v67, v76, s52
	ds_read_u16 v67, v164
	ds_read_u16 v76, v164 offset:2176
	ds_read_u16 v72, v165
	ds_read_u16 v77, v165 offset:2176
	ds_read_u16 v73, v166
	ds_read_u16 v98, v166 offset:2176
	ds_read_u16 v197, v165 offset:4352
	ds_read_u16 v99, v167
	ds_read_u16 v148, v167 offset:2176
	ds_read_u16 v184, v168
	ds_read_u16 v188, v168 offset:2176
	ds_read_u16 v185, v169
	ds_read_u16 v198, v168 offset:4352
	ds_read_u16 v199, v167 offset:4352
	ds_read_u16 v200, v166 offset:4352
	s_waitcnt lgkmcnt(7)
	v_perm_b32 v73, v99, v73, s52
	ds_read_u16 v201, v164 offset:4352
	v_perm_b32 v72, v72, v67, s52
	s_waitcnt lgkmcnt(7)
	v_perm_b32 v181, v148, v98, s52
	v_perm_b32 v180, v77, v76, s52
	ds_read2_b32 v[148:149], v66 offset0:128 offset1:144
	ds_read_u16 v66, v169 offset:2176
	ds_read_u16 v67, v170
	ds_read_u16 v98, v170 offset:2176
	ds_read_u16 v76, v171
	ds_read_u16 v99, v171 offset:2176
	ds_read_u16 v202, v171 offset:4352
	ds_read_u16 v203, v170 offset:4352
	ds_read_u16 v204, v169 offset:4352
	s_waitcnt lgkmcnt(4)
	v_perm_b32 v77, v76, v67, s52
	v_perm_b32 v76, v185, v184, s52
	s_waitcnt lgkmcnt(3)
	v_perm_b32 v185, v99, v98, s52
	v_mov_b32_e32 v98, v103
	v_mov_b32_e32 v99, v103
	v_perm_b32 v184, v66, v188, s52
	v_lshlrev_b32_e32 v67, 16, v70
	v_mfma_f32_16x16x32_bf16 v[96:99], v[92:95], v[96:99], 0
	v_lshlrev_b32_e32 v66, 16, v71
	v_lshlrev_b32_e32 v71, 16, v178
	v_lshlrev_b32_e32 v70, 16, v179
	v_mov_b32_e32 v178, v103
	v_mov_b32_e32 v179, v103
	s_nop 2
	v_cvt_pk_bf16_f32 v188, v96, v97
	v_cvt_pk_bf16_f32 v189, v98, v99
	v_mov_b32_e32 v196, v151
	v_mfma_f32_16x16x32_bf16 v[80:83], v[88:91], v[84:87], 0
	v_mfma_f32_16x16x32_bf16 v[96:99], v[88:91], v[188:191], 0
	s_nop 6
	v_sub_f32_e32 v129, v129, v82
	v_pk_add_f32 v[66:67], v[66:67], v[96:97] neg_lo:[0,1] neg_hi:[0,1]
	v_pk_add_f32 v[70:71], v[70:71], v[98:99] neg_lo:[0,1] neg_hi:[0,1]
	v_mfma_f32_16x16x32_bf16 v[96:99], v[92:95], v[176:179], 0
	v_mul_f32_e64 v66, v150, v66
	v_mul_f32_e64 v67, v150, v67
	v_pk_mul_f32 v[70:71], v[150:151], v[70:71] op_sel_hi:[0,1]
	v_cvt_pk_bf16_f32 v66, v66, v67
	v_cvt_pk_bf16_f32 v67, v70, v71
	v_lshl_add_u64 v[70:71], s[20:21], 0, v[104:105]
	s_nop 1
	v_cvt_pk_bf16_f32 v176, v96, v97
	v_cvt_pk_bf16_f32 v177, v98, v99
	v_add_co_u32_e32 v194, vcc, s53, v70
	s_nop 0
	v_mfma_f32_16x16x32_bf16 v[96:99], v[88:91], v[176:179], 0
	v_addc_co_u32_e32 v195, vcc, 0, v71, vcc
	v_lshl_add_u64 v[192:193], v[70:71], 0, s[36:37]
	global_store_dwordx2 v[194:195], v[66:67], off offset:-4096
	v_lshlrev_b32_e32 v67, 16, v187
	v_lshlrev_b32_e32 v66, 16, v182
	v_lshlrev_b32_e32 v71, 16, v183
	v_lshlrev_b32_e32 v70, 16, v186
	v_mov_b32_e32 v182, v103
	v_mov_b32_e32 v183, v103
	v_pk_add_f32 v[66:67], v[66:67], v[96:97] neg_lo:[0,1] neg_hi:[0,1]
	v_pk_add_f32 v[70:71], v[70:71], v[98:99] neg_lo:[0,1] neg_hi:[0,1]
	v_mfma_f32_16x16x32_bf16 v[96:99], v[92:95], v[180:183], 0
	v_mov_b32_e32 v186, v103
	v_mov_b32_e32 v187, v103
	v_pk_mul_f32 v[66:67], v[196:197], v[66:67] op_sel_hi:[0,1]
	v_pk_mul_f32 v[70:71], v[196:197], v[70:71] op_sel_hi:[0,1]
	v_mfma_f32_16x16x32_bf16 v[92:95], v[92:95], v[184:187], 0
	s_nop 2
	v_cvt_pk_bf16_f32 v96, v96, v97
	v_cvt_pk_bf16_f32 v97, v98, v99
	v_mov_b32_e32 v98, v103
	v_mov_b32_e32 v99, v103
	v_cvt_pk_bf16_f32 v66, v66, v67
	v_cvt_pk_bf16_f32 v67, v70, v71
	v_mfma_f32_16x16x32_bf16 v[180:183], v[88:91], v[96:99], 0
	global_store_dwordx2 v[192:193], v[66:67], off offset:512
	v_lshlrev_b32_e32 v67, 16, v197
	v_lshlrev_b32_e32 v66, 16, v201
	v_lshlrev_b32_e32 v71, 16, v199
	v_lshlrev_b32_e32 v70, 16, v200
	v_cvt_pk_bf16_f32 v92, v92, v93
	v_cvt_pk_bf16_f32 v93, v94, v95
	v_mov_b32_e32 v94, v103
	v_mov_b32_e32 v95, v103
	v_pk_add_f32 v[66:67], v[66:67], v[180:181] neg_lo:[0,1] neg_hi:[0,1]
	v_pk_add_f32 v[70:71], v[70:71], v[182:183] neg_lo:[0,1] neg_hi:[0,1]
	v_mfma_f32_16x16x32_bf16 v[88:91], v[88:91], v[92:95], 0
	v_mul_f32_e64 v66, v148, v66
	v_mul_f32_e64 v67, v148, v67
	v_pk_mul_f32 v[70:71], v[148:149], v[70:71] op_sel_hi:[0,1]
	v_cvt_pk_bf16_f32 v66, v66, v67
	v_cvt_pk_bf16_f32 v67, v70, v71
	global_store_dwordx2 v[192:193], v[66:67], off offset:1024
	s_waitcnt lgkmcnt(0)
	v_lshlrev_b32_e32 v67, 16, v204
	v_lshlrev_b32_e32 v66, 16, v198
	v_pk_add_f32 v[66:67], v[66:67], v[88:89] neg_lo:[0,1] neg_hi:[0,1]
	v_mov_b32_e32 v88, v149
	v_pk_mul_f32 v[70:71], v[88:89], v[66:67] op_sel_hi:[0,1]
	v_lshlrev_b32_e32 v67, 16, v202
	v_lshlrev_b32_e32 v66, 16, v203
	v_pk_add_f32 v[90:91], v[66:67], v[90:91] neg_lo:[0,1] neg_hi:[0,1]
	v_mov_b32_e32 v66, v103
	v_mov_b32_e32 v67, v103
	v_pk_mul_f32 v[90:91], v[88:89], v[90:91] op_sel_hi:[0,1]
	v_cvt_pk_bf16_f32 v70, v70, v71
	v_cvt_pk_bf16_f32 v71, v90, v91
	global_store_dwordx2 v[192:193], v[70:71], off offset:1536
	v_mov_b32_e32 v70, v103
	v_mov_b32_e32 v71, v103
	v_mfma_f32_16x16x32_bf16 v[180:183], v[64:67], v[84:87], 0
	v_sub_f32_e32 v89, v175, v83
	v_sub_f32_e32 v127, v127, v81
	v_sub_f32_e32 v125, v125, v80
	s_nop 4
	v_pk_add_f32 v[90:91], v[142:143], v[180:181] neg_lo:[0,1] neg_hi:[0,1]
	v_pk_add_f32 v[142:143], v[74:75], v[182:183] neg_lo:[0,1] neg_hi:[0,1]
	v_mfma_f32_16x16x32_bf16 v[180:183], v[68:71], v[84:87], 0
	v_mov_b32_e32 v74, v103
	v_mov_b32_e32 v75, v103
	v_cvt_pk_bf16_f32 v80, v90, v91
	v_cvt_pk_bf16_f32 v81, v142, v143
	v_mfma_f32_16x16x32_bf16 v[184:187], v[72:75], v[84:87], 0
	s_nop 2
	v_add_f32_e64 v180, v78, -v180
	v_add_f32_e64 v181, v79, -v181
	v_mov_b32_e32 v78, v103
	v_mov_b32_e32 v79, v103
	v_pk_add_f32 v[140:141], v[140:141], v[182:183] neg_lo:[0,1] neg_hi:[0,1]
	v_pk_add_f32 v[138:139], v[138:139], v[184:185] neg_lo:[0,1] neg_hi:[0,1]
	v_mfma_f32_16x16x32_bf16 v[84:87], v[76:79], v[84:87], 0
	v_add_f32_e64 v136, v136, -v186
	v_add_f32_e64 v137, v137, -v187
	v_cvt_pk_bf16_f32 v82, v180, v181
	v_cvt_pk_bf16_f32 v83, v140, v141
	s_nop 3
	v_pk_add_f32 v[84:85], v[134:135], v[84:85] neg_lo:[0,1] neg_hi:[0,1]
	v_pk_add_f32 v[86:87], v[130:131], v[86:87] neg_lo:[0,1] neg_hi:[0,1]
	v_lshl_add_u64 v[90:91], s[10:11], 0, v[106:107]
	global_store_dwordx4 v[90:91], v[80:83], off sc0 sc1
	s_nop 1
	v_cvt_pk_bf16_f32 v80, v138, v139
	v_cvt_pk_bf16_f32 v81, v136, v137
	v_cvt_pk_bf16_f32 v82, v84, v85
	v_cvt_pk_bf16_f32 v83, v86, v87
	v_lshl_add_u64 v[84:85], s[10:11], 0, v[108:109]
	global_store_dwordx4 v[84:85], v[80:83], off sc0 sc1
	s_nop 1
	v_cvt_pk_bf16_f32 v80, v125, v127
	v_cvt_pk_bf16_f32 v81, v129, v89
	global_store_dwordx2 v[194:195], v[80:81], off
	v_mfma_f32_16x16x32_bf16 v[80:83], v[64:67], v[188:191], 0
	s_nop 7
	v_pk_add_f32 v[80:81], v[110:111], v[80:81] neg_lo:[0,1] neg_hi:[0,1]
	s_nop 0
	v_pk_mul_f32 v[84:85], v[150:151], v[80:81] op_sel_hi:[0,1]
	v_pk_add_f32 v[80:81], v[112:113], v[82:83] neg_lo:[0,1] neg_hi:[0,1]
	s_nop 0
	v_pk_mul_f32 v[86:87], v[150:151], v[80:81] op_sel_hi:[0,1]
	v_mfma_f32_16x16x32_bf16 v[80:83], v[68:71], v[188:191], 0
	s_nop 7
	v_pk_add_f32 v[80:81], v[80:81], 0 op_sel_hi:[1,0] neg_lo:[1,0] neg_hi:[1,0]
	s_nop 0
	v_pk_mul_f32 v[90:91], v[150:151], v[80:81] op_sel_hi:[0,1]
	v_pk_add_f32 v[80:81], v[82:83], 0 op_sel_hi:[1,0] neg_lo:[1,0] neg_hi:[1,0]
	s_nop 0
	v_pk_mul_f32 v[130:131], v[150:151], v[80:81] op_sel_hi:[0,1]
	v_mfma_f32_16x16x32_bf16 v[80:83], v[72:75], v[188:191], 0
	s_nop 7
	v_pk_add_f32 v[80:81], v[80:81], 0 op_sel_hi:[1,0] neg_lo:[1,0] neg_hi:[1,0]
	s_nop 0
	v_pk_mul_f32 v[134:135], v[150:151], v[80:81] op_sel_hi:[0,1]
	v_pk_add_f32 v[80:81], v[82:83], 0 op_sel_hi:[1,0] neg_lo:[1,0] neg_hi:[1,0]
	s_nop 0
	v_pk_mul_f32 v[136:137], v[150:151], v[80:81] op_sel_hi:[0,1]
	v_mfma_f32_16x16x32_bf16 v[80:83], v[76:79], v[188:191], 0
	s_nop 7
	v_pk_add_f32 v[80:81], v[80:81], 0 op_sel_hi:[1,0] neg_lo:[1,0] neg_hi:[1,0]
	s_nop 0
	v_pk_mul_f32 v[138:139], v[150:151], v[80:81] op_sel_hi:[0,1]
	v_pk_add_f32 v[80:81], v[82:83], 0 op_sel_hi:[1,0] neg_lo:[1,0] neg_hi:[1,0]
	v_cvt_pk_bf16_f32 v82, v90, v91
	v_pk_mul_f32 v[140:141], v[150:151], v[80:81] op_sel_hi:[0,1]
	v_cvt_pk_bf16_f32 v80, v84, v85
	v_cvt_pk_bf16_f32 v81, v86, v87
	v_cvt_pk_bf16_f32 v83, v130, v131
	v_lshl_add_u64 v[84:85], s[20:21], 0, v[106:107]
	global_store_dwordx4 v[84:85], v[80:83], off sc0 sc1
	s_nop 1
	v_cvt_pk_bf16_f32 v80, v134, v135
	v_cvt_pk_bf16_f32 v81, v136, v137
	v_cvt_pk_bf16_f32 v82, v138, v139
	v_cvt_pk_bf16_f32 v83, v140, v141
	global_store_dwordx4 v[84:85], v[80:83], off offset:1024 sc0 sc1
	s_nop 1
	v_mfma_f32_16x16x32_bf16 v[80:83], v[64:67], v[176:179], 0
	s_nop 7
	v_pk_add_f32 v[80:81], v[80:81], 0 op_sel_hi:[1,0] neg_lo:[1,0] neg_hi:[1,0]
	s_nop 0
	v_pk_mul_f32 v[86:87], v[196:197], v[80:81] op_sel_hi:[0,1]
	v_pk_add_f32 v[80:81], v[82:83], 0 op_sel_hi:[1,0] neg_lo:[1,0] neg_hi:[1,0]
	s_nop 0
	v_pk_mul_f32 v[90:91], v[196:197], v[80:81] op_sel_hi:[0,1]
	v_mfma_f32_16x16x32_bf16 v[80:83], v[68:71], v[176:179], 0
	s_nop 7
	v_pk_add_f32 v[80:81], v[114:115], v[80:81] neg_lo:[0,1] neg_hi:[0,1]
	s_nop 0
	v_pk_mul_f32 v[130:131], v[196:197], v[80:81] op_sel_hi:[0,1]
	v_pk_add_f32 v[80:81], v[116:117], v[82:83] neg_lo:[0,1] neg_hi:[0,1]
	s_nop 0
	v_pk_mul_f32 v[134:135], v[196:197], v[80:81] op_sel_hi:[0,1]
	v_mfma_f32_16x16x32_bf16 v[80:83], v[72:75], v[176:179], 0
	s_nop 7
	v_pk_add_f32 v[80:81], v[80:81], 0 op_sel_hi:[1,0] neg_lo:[1,0] neg_hi:[1,0]
	s_nop 0
	v_pk_mul_f32 v[136:137], v[196:197], v[80:81] op_sel_hi:[0,1]
	v_pk_add_f32 v[80:81], v[82:83], 0 op_sel_hi:[1,0] neg_lo:[1,0] neg_hi:[1,0]
	s_nop 0
	v_pk_mul_f32 v[138:139], v[196:197], v[80:81] op_sel_hi:[0,1]
	v_mfma_f32_16x16x32_bf16 v[80:83], v[76:79], v[176:179], 0
	s_nop 7
	v_pk_add_f32 v[80:81], v[80:81], 0 op_sel_hi:[1,0] neg_lo:[1,0] neg_hi:[1,0]
	s_nop 0
	v_pk_mul_f32 v[140:141], v[196:197], v[80:81] op_sel_hi:[0,1]
	v_pk_add_f32 v[80:81], v[82:83], 0 op_sel_hi:[1,0] neg_lo:[1,0] neg_hi:[1,0]
	v_cvt_pk_bf16_f32 v82, v130, v131
	v_pk_mul_f32 v[142:143], v[196:197], v[80:81] op_sel_hi:[0,1]
	v_cvt_pk_bf16_f32 v80, v86, v87
	v_cvt_pk_bf16_f32 v81, v90, v91
	v_cvt_pk_bf16_f32 v83, v134, v135
	global_store_dwordx4 v[84:85], v[80:83], off offset:2048 sc0 sc1
	s_nop 1
	v_cvt_pk_bf16_f32 v80, v136, v137
	v_cvt_pk_bf16_f32 v81, v138, v139
	v_cvt_pk_bf16_f32 v82, v140, v141
	v_cvt_pk_bf16_f32 v83, v142, v143
	global_store_dwordx4 v[84:85], v[80:83], off offset:3072 sc0 sc1
	v_add_co_u32_e32 v84, vcc, s28, v84
	s_nop 0
	v_mfma_f32_16x16x32_bf16 v[80:83], v[64:67], v[96:99], 0
	v_addc_co_u32_e32 v85, vcc, 0, v85, vcc
	v_mfma_f32_16x16x32_bf16 v[64:67], v[64:67], v[92:95], 0
	s_nop 5
	v_add_f32_e64 v80, -v80, 0
	v_add_f32_e64 v81, -v81, 0
	v_pk_add_f32 v[64:65], v[64:65], 0 op_sel_hi:[1,0] neg_lo:[1,0] neg_hi:[1,0]
	v_pk_mul_f32 v[86:87], v[148:149], v[80:81] op_sel_hi:[0,1]
	v_pk_add_f32 v[80:81], v[82:83], 0 op_sel_hi:[1,0] neg_lo:[1,0] neg_hi:[1,0]
	s_nop 0
	v_pk_mul_f32 v[90:91], v[148:149], v[80:81] op_sel_hi:[0,1]
	v_mfma_f32_16x16x32_bf16 v[80:83], v[68:71], v[96:99], 0
	s_nop 7
	v_pk_add_f32 v[80:81], v[80:81], 0 op_sel_hi:[1,0] neg_lo:[1,0] neg_hi:[1,0]
	s_nop 0
	v_pk_mul_f32 v[130:131], v[148:149], v[80:81] op_sel_hi:[0,1]
	v_pk_add_f32 v[80:81], v[82:83], 0 op_sel_hi:[1,0] neg_lo:[1,0] neg_hi:[1,0]
	s_nop 0
	v_pk_mul_f32 v[134:135], v[148:149], v[80:81] op_sel_hi:[0,1]
	v_mfma_f32_16x16x32_bf16 v[80:83], v[72:75], v[96:99], 0
	s_nop 7
	v_pk_add_f32 v[80:81], v[114:115], v[80:81] neg_lo:[0,1] neg_hi:[0,1]
	s_nop 0
	v_pk_mul_f32 v[136:137], v[148:149], v[80:81] op_sel_hi:[0,1]
	v_pk_add_f32 v[80:81], v[118:119], v[82:83] neg_lo:[0,1] neg_hi:[0,1]
	s_nop 0
	v_pk_mul_f32 v[138:139], v[148:149], v[80:81] op_sel_hi:[0,1]
	v_mfma_f32_16x16x32_bf16 v[80:83], v[76:79], v[96:99], 0
	s_nop 7
	v_pk_add_f32 v[80:81], v[80:81], 0 op_sel_hi:[1,0] neg_lo:[1,0] neg_hi:[1,0]
	s_nop 0
	v_pk_mul_f32 v[96:97], v[148:149], v[80:81] op_sel_hi:[0,1]
	v_pk_add_f32 v[80:81], v[82:83], 0 op_sel_hi:[1,0] neg_lo:[1,0] neg_hi:[1,0]
	v_cvt_pk_bf16_f32 v82, v130, v131
	v_pk_mul_f32 v[98:99], v[148:149], v[80:81] op_sel_hi:[0,1]
	v_cvt_pk_bf16_f32 v80, v86, v87
	v_cvt_pk_bf16_f32 v81, v90, v91
	v_cvt_pk_bf16_f32 v83, v134, v135
	global_store_dwordx4 v[84:85], v[80:83], off sc0 sc1
	s_nop 1
	v_cvt_pk_bf16_f32 v80, v136, v137
	v_cvt_pk_bf16_f32 v81, v138, v139
	v_cvt_pk_bf16_f32 v82, v96, v97
	v_cvt_pk_bf16_f32 v83, v98, v99
	global_store_dwordx4 v[84:85], v[80:83], off offset:1024 sc0 sc1
	s_nop 1
	v_pk_mul_f32 v[80:81], v[88:89], v[64:65] op_sel_hi:[0,1]
	v_pk_add_f32 v[64:65], v[66:67], 0 op_sel_hi:[1,0] neg_lo:[1,0] neg_hi:[1,0]
	s_nop 0
	v_pk_mul_f32 v[82:83], v[88:89], v[64:65] op_sel_hi:[0,1]
	v_mfma_f32_16x16x32_bf16 v[64:67], v[68:71], v[92:95], 0
	s_nop 7
	v_pk_add_f32 v[64:65], v[64:65], 0 op_sel_hi:[1,0] neg_lo:[1,0] neg_hi:[1,0]
	s_nop 0
	v_pk_mul_f32 v[68:69], v[88:89], v[64:65] op_sel_hi:[0,1]
	v_pk_add_f32 v[64:65], v[66:67], 0 op_sel_hi:[1,0] neg_lo:[1,0] neg_hi:[1,0]
	s_nop 0
	v_pk_mul_f32 v[70:71], v[88:89], v[64:65] op_sel_hi:[0,1]
	v_mfma_f32_16x16x32_bf16 v[64:67], v[72:75], v[92:95], 0
	s_nop 7
	v_pk_add_f32 v[64:65], v[64:65], 0 op_sel_hi:[1,0] neg_lo:[1,0] neg_hi:[1,0]
	s_nop 0
	v_pk_mul_f32 v[72:73], v[88:89], v[64:65] op_sel_hi:[0,1]
	v_pk_add_f32 v[64:65], v[66:67], 0 op_sel_hi:[1,0] neg_lo:[1,0] neg_hi:[1,0]
	s_nop 0
	v_pk_mul_f32 v[74:75], v[88:89], v[64:65] op_sel_hi:[0,1]
	v_mfma_f32_16x16x32_bf16 v[64:67], v[76:79], v[92:95], 0
	s_nop 7
	v_pk_add_f32 v[64:65], v[114:115], v[64:65] neg_lo:[0,1] neg_hi:[0,1]
	s_nop 0
	v_pk_mul_f32 v[76:77], v[88:89], v[64:65] op_sel_hi:[0,1]
	v_pk_add_f32 v[64:65], v[120:121], v[66:67] neg_lo:[0,1] neg_hi:[0,1]
	v_cvt_pk_bf16_f32 v66, v68, v69
	v_pk_mul_f32 v[78:79], v[88:89], v[64:65] op_sel_hi:[0,1]
	v_cvt_pk_bf16_f32 v64, v80, v81
	v_cvt_pk_bf16_f32 v65, v82, v83
	v_cvt_pk_bf16_f32 v67, v70, v71
	global_store_dwordx4 v[84:85], v[64:67], off offset:2048 sc0 sc1
	s_nop 1
	v_cvt_pk_bf16_f32 v64, v72, v73
	v_cvt_pk_bf16_f32 v65, v74, v75
	v_cvt_pk_bf16_f32 v66, v76, v77
	v_cvt_pk_bf16_f32 v67, v78, v79
	global_store_dwordx4 v[84:85], v[64:67], off offset:3072 sc0 sc1
	s_waitcnt lgkmcnt(0)
	s_cbranch_scc0 .LBB0_837
